# P9 conv epilogue: gate weights loaded first, counted waits per conv instead of one drain
# speedup vs baseline: 1.0072x; 1.0037x over previous
; __device__ __forceinline__ float dpp_ror1(float v) { return __int_as_float(__builtin_amdgcn_update_dpp(0, __float_as_int(v), 0x121, 0xf, 0xf, false)); }
; __device__ __forceinline__ float dpp_rol1(float v) { return __int_as_float(__builtin_amdgcn_update_dpp(0, __float_as_int(v), 0x12F, 0xf, 0xf, false)); }
;     __device__ __forceinline__ void tile(const f32x4 (&acc)[2][2][4][2], const Unit& u, int wr, int wc, int fr, int fq) const {
;     ...
;             const int cv = 128 * u.pn + 32 * wc + 16 * n + 4 * fq, cg = FF + cv;
;             const f32x4 wv0 = *(const f32x4*)(cw + cv), wv1 = *(const f32x4*)(cw + F2 + cv), wv2 = *(const f32x4*)(cw + 2 * F2 + cv), bv = *(const f32x4*)(cb + cv);
;             const f32x4 wg0 = *(const f32x4*)(cw + cg), wg1 = *(const f32x4*)(cw + F2 + cg), wg2 = *(const f32x4*)(cw + 2 * F2 + cg), bg = *(const f32x4*)(cb + cg);
; #pragma unroll
;             for (int ai = 0; ai < 2; ++ai)
; #pragma unroll
;                 for (int m = 0; m < 4; ++m) {
;                     f32x4 r;
; #pragma unroll
;                     for (int i = 0; i < 4; ++i) {
;                         const float xv = acc[ai][0][m][n][i], xg = acc[ai][1][m][n][i];
;                         const float uv = m > 0 ? acc[ai][0][m > 0 ? m - 1 : 0][n][i] : 0.f, ug = m > 0 ? acc[ai][1][m > 0 ? m - 1 : 0][n][i] : 0.f;
;                         const float dv = m < 3 ? acc[ai][0][m < 3 ? m + 1 : 3][n][i] : 0.f, dg = m < 3 ? acc[ai][1][m < 3 ? m + 1 : 3][n][i] : 0.f;
;                         const float pv = dpp_ror1(fr == 15 ? uv : xv), pg = dpp_ror1(fr == 15 ? ug : xg);
;                         const float nv = dpp_rol1(fr == 0 ? dv : xv), ng = dpp_rol1(fr == 0 ? dg : xg);
;                         const float yv = wv0[i] * pv + wv1[i] * xv + wv2[i] * nv + bv[i];
;                         const float yg = wg0[i] * pg + wg1[i] * xg + wg2[i] * ng + bg[i];
.LBB0_1802:
	v_lshl_or_b32 v170, s33, 7, v204
	v_lshlrev_b32_e32 v171, 2, v170
	v_add_u32_e32 v172, 0x5800, v171
	global_load_dwordx4 v[136:139], v172, s[56:57]
	global_load_dwordx4 v[140:143], v172, s[12:13]
	global_load_dwordx4 v[144:147], v172, s[14:15]
	global_load_dwordx4 v[148:151], v172, s[58:59]
	global_load_dwordx4 v[120:123], v171, s[56:57]
	global_load_dwordx4 v[124:127], v171, s[12:13]
	global_load_dwordx4 v[128:131], v171, s[14:15]
	global_load_dwordx4 v[132:135], v171, s[58:59]
	global_load_dwordx4 v[246:249], v172, s[56:57] offset:64
	global_load_dwordx4 v[250:253], v172, s[12:13] offset:64
	global_load_dwordx4 v[208:211], v172, s[14:15] offset:64
	global_load_dwordx4 v[212:215], v172, s[58:59] offset:64
	global_load_dwordx4 v[230:233], v171, s[56:57] offset:64
	global_load_dwordx4 v[234:237], v171, s[12:13] offset:64
	global_load_dwordx4 v[238:241], v171, s[14:15] offset:64
	global_load_dwordx4 v[242:245], v171, s[58:59] offset:64
	s_lshl_b32 s17, s26, 8
	v_and_b32_e32 v173, 64, v195
	v_and_b32_e32 v174, 15, v195
	v_lshl_add_u32 v173, v174, 2, v173
	v_add_u32_e32 v173, s17, v173
	v_mul_u32_u24_e32 v173, 0x2c00, v173
	v_lshl_add_u32 v173, v170, 1, v173
	v_add_u32_e32 v174, 0x160000, v173
	s_waitcnt vmcnt(12)
	v_mov_b32_dpp v216, v96 row_shr:1 row_mask:0xf bank_mask:0xf bound_ctrl:1
	v_mov_b32_dpp v217, v97 row_shr:1 row_mask:0xf bank_mask:0xf bound_ctrl:1
	v_mov_b32_dpp v218, v98 row_shr:1 row_mask:0xf bank_mask:0xf bound_ctrl:1
	v_mov_b32_dpp v219, v99 row_shr:1 row_mask:0xf bank_mask:0xf bound_ctrl:1
	v_mov_b32_dpp v220, v152 row_shl:1 row_mask:0xf bank_mask:0xf bound_ctrl:1
	v_mov_b32_dpp v221, v153 row_shl:1 row_mask:0xf bank_mask:0xf bound_ctrl:1
	v_mov_b32_dpp v222, v154 row_shl:1 row_mask:0xf bank_mask:0xf bound_ctrl:1
	v_mov_b32_dpp v223, v155 row_shl:1 row_mask:0xf bank_mask:0xf bound_ctrl:1
	v_pk_mul_f32 v[176:177], v[152:153], v[140:141]
	v_pk_mul_f32 v[178:179], v[154:155], v[142:143]
	v_pk_mul_f32 v[180:181], v[112:113], v[140:141]
	v_pk_mul_f32 v[182:183], v[114:115], v[142:143]
	v_pk_mul_f32 v[184:185], v[104:105], v[140:141]
	v_pk_mul_f32 v[186:187], v[106:107], v[142:143]
	v_pk_mul_f32 v[224:225], v[96:97], v[140:141]
	v_pk_mul_f32 v[226:227], v[98:99], v[142:143]
	v_pk_fma_f32 v[176:177], v[136:137], v[216:217], v[176:177]
	v_pk_fma_f32 v[178:179], v[138:139], v[218:219], v[178:179]
	v_pk_fma_f32 v[180:181], v[136:137], v[152:153], v[180:181]
	v_pk_fma_f32 v[182:183], v[138:139], v[154:155], v[182:183]
	v_pk_fma_f32 v[184:185], v[136:137], v[112:113], v[184:185]
	v_pk_fma_f32 v[186:187], v[138:139], v[114:115], v[186:187]
	v_pk_fma_f32 v[224:225], v[136:137], v[104:105], v[224:225]
	v_pk_fma_f32 v[226:227], v[138:139], v[106:107], v[226:227]
	v_pk_fma_f32 v[176:177], v[144:145], v[112:113], v[176:177]
	v_pk_fma_f32 v[178:179], v[146:147], v[114:115], v[178:179]
	v_pk_fma_f32 v[180:181], v[144:145], v[104:105], v[180:181]
	v_pk_fma_f32 v[182:183], v[146:147], v[106:107], v[182:183]
	v_pk_fma_f32 v[184:185], v[144:145], v[96:97], v[184:185]
	v_pk_fma_f32 v[186:187], v[146:147], v[98:99], v[186:187]
	v_pk_fma_f32 v[224:225], v[144:145], v[220:221], v[224:225]
	v_pk_fma_f32 v[226:227], v[146:147], v[222:223], v[226:227]
	v_pk_add_f32 v[176:177], v[148:149], v[176:177]
	v_pk_add_f32 v[178:179], v[150:151], v[178:179]
	v_pk_add_f32 v[180:181], v[148:149], v[180:181]
	v_pk_add_f32 v[182:183], v[150:151], v[182:183]
	v_pk_add_f32 v[184:185], v[148:149], v[184:185]
	v_pk_add_f32 v[186:187], v[150:151], v[186:187]
	v_pk_add_f32 v[224:225], v[148:149], v[224:225]
	v_pk_add_f32 v[226:227], v[150:151], v[226:227]
	s_waitcnt vmcnt(8)
	v_mov_b32_dpp v216, v100 row_shr:1 row_mask:0xf bank_mask:0xf bound_ctrl:1
	v_mov_b32_dpp v217, v101 row_shr:1 row_mask:0xf bank_mask:0xf bound_ctrl:1
	v_mov_b32_dpp v218, v102 row_shr:1 row_mask:0xf bank_mask:0xf bound_ctrl:1
	v_mov_b32_dpp v219, v103 row_shr:1 row_mask:0xf bank_mask:0xf bound_ctrl:1
	v_mov_b32_dpp v220, v156 row_shl:1 row_mask:0xf bank_mask:0xf bound_ctrl:1
	v_mov_b32_dpp v221, v157 row_shl:1 row_mask:0xf bank_mask:0xf bound_ctrl:1
	v_mov_b32_dpp v222, v158 row_shl:1 row_mask:0xf bank_mask:0xf bound_ctrl:1
	v_mov_b32_dpp v223, v159 row_shl:1 row_mask:0xf bank_mask:0xf bound_ctrl:1
	v_pk_mul_f32 v[152:153], v[156:157], v[124:125]
	v_pk_mul_f32 v[154:155], v[158:159], v[126:127]
	v_pk_mul_f32 v[112:113], v[116:117], v[124:125]
	v_pk_mul_f32 v[114:115], v[118:119], v[126:127]
	v_pk_mul_f32 v[104:105], v[108:109], v[124:125]
	v_pk_mul_f32 v[106:107], v[110:111], v[126:127]
	v_pk_mul_f32 v[96:97], v[100:101], v[124:125]
	v_pk_mul_f32 v[98:99], v[102:103], v[126:127]
	v_pk_fma_f32 v[152:153], v[120:121], v[216:217], v[152:153]
	v_pk_fma_f32 v[154:155], v[122:123], v[218:219], v[154:155]
	v_pk_fma_f32 v[112:113], v[120:121], v[156:157], v[112:113]
	v_pk_fma_f32 v[114:115], v[122:123], v[158:159], v[114:115]
	v_pk_fma_f32 v[104:105], v[120:121], v[116:117], v[104:105]
	v_pk_fma_f32 v[106:107], v[122:123], v[118:119], v[106:107]
	v_pk_fma_f32 v[96:97], v[120:121], v[108:109], v[96:97]
	v_pk_fma_f32 v[98:99], v[122:123], v[110:111], v[98:99]
	v_pk_fma_f32 v[152:153], v[128:129], v[116:117], v[152:153]
	v_pk_fma_f32 v[154:155], v[130:131], v[118:119], v[154:155]
	v_pk_fma_f32 v[112:113], v[128:129], v[108:109], v[112:113]
	v_pk_fma_f32 v[114:115], v[130:131], v[110:111], v[114:115]
	v_pk_fma_f32 v[104:105], v[128:129], v[100:101], v[104:105]
	v_pk_fma_f32 v[106:107], v[130:131], v[102:103], v[106:107]
	v_pk_fma_f32 v[96:97], v[128:129], v[220:221], v[96:97]
	v_pk_fma_f32 v[98:99], v[130:131], v[222:223], v[98:99]
	v_pk_add_f32 v[152:153], v[132:133], v[152:153]
; __device__ __forceinline__ void st_bf4(bf16_t* p, f32x4 v) { u32x2 w; w.x = pk2(v[0], v[1]); w.y = pk2(v[2], v[3]); *(u32x2*)p = w; }
; __device__ __forceinline__ float sigmoidf_(float x) { return __builtin_amdgcn_rcpf(1.f + __expf(-x)); }
; __device__ __forceinline__ float dpp_ror1(float v) { return __int_as_float(__builtin_amdgcn_update_dpp(0, __float_as_int(v), 0x121, 0xf, 0xf, false)); }
; __device__ __forceinline__ float dpp_rol1(float v) { return __int_as_float(__builtin_amdgcn_update_dpp(0, __float_as_int(v), 0x12F, 0xf, 0xf, false)); }
;     __device__ __forceinline__ void tile(const f32x4 (&acc)[2][2][4][2], const Unit& u, int wr, int wc, int fr, int fq) const {
;     ...
;                         const float xv = acc[ai][0][m][n][i], xg = acc[ai][1][m][n][i];
;                         const float uv = m > 0 ? acc[ai][0][m > 0 ? m - 1 : 0][n][i] : 0.f, ug = m > 0 ? acc[ai][1][m > 0 ? m - 1 : 0][n][i] : 0.f;
;                         const float dv = m < 3 ? acc[ai][0][m < 3 ? m + 1 : 3][n][i] : 0.f, dg = m < 3 ? acc[ai][1][m < 3 ? m + 1 : 3][n][i] : 0.f;
;                         const float pv = dpp_ror1(fr == 15 ? uv : xv), pg = dpp_ror1(fr == 15 ? ug : xg);
;                         const float nv = dpp_rol1(fr == 0 ? dv : xv), ng = dpp_rol1(fr == 0 ? dg : xg);
;                         const float yv = wv0[i] * pv + wv1[i] * xv + wv2[i] * nv + bv[i];
;                         const float yg = wg0[i] * pg + wg1[i] * xg + wg2[i] * ng + bg[i];
;                         r[i] = yg * sigmoidf_(yg) * yv;
;                     }
;                     st_bf4(ACT + (size_t)(u.pm * BM + ai * HALF + wr * 64 + m * 16 + fr) * FF + cv, r);
	v_pk_add_f32 v[154:155], v[134:135], v[154:155]
	v_pk_add_f32 v[112:113], v[132:133], v[112:113]
	v_pk_add_f32 v[114:115], v[134:135], v[114:115]
	v_pk_add_f32 v[104:105], v[132:133], v[104:105]
	v_pk_add_f32 v[106:107], v[134:135], v[106:107]
	v_pk_add_f32 v[96:97], v[132:133], v[96:97]
	v_pk_add_f32 v[98:99], v[134:135], v[98:99]
	v_mul_f32_e32 v156, 0xbfb8aa3b, v176
	v_mul_f32_e32 v157, 0xbfb8aa3b, v177
	v_mul_f32_e32 v158, 0xbfb8aa3b, v178
	v_mul_f32_e32 v159, 0xbfb8aa3b, v179
	v_mul_f32_e32 v116, 0xbfb8aa3b, v180
	v_mul_f32_e32 v117, 0xbfb8aa3b, v181
	v_mul_f32_e32 v118, 0xbfb8aa3b, v182
	v_mul_f32_e32 v119, 0xbfb8aa3b, v183
	v_mul_f32_e32 v108, 0xbfb8aa3b, v184
	v_mul_f32_e32 v109, 0xbfb8aa3b, v185
	v_mul_f32_e32 v110, 0xbfb8aa3b, v186
	v_mul_f32_e32 v111, 0xbfb8aa3b, v187
	v_mul_f32_e32 v100, 0xbfb8aa3b, v224
	v_mul_f32_e32 v101, 0xbfb8aa3b, v225
	v_mul_f32_e32 v102, 0xbfb8aa3b, v226
	v_mul_f32_e32 v103, 0xbfb8aa3b, v227
	v_exp_f32_e32 v156, v156
	v_exp_f32_e32 v157, v157
	v_exp_f32_e32 v158, v158
	v_exp_f32_e32 v159, v159
	v_exp_f32_e32 v116, v116
	v_exp_f32_e32 v117, v117
	v_exp_f32_e32 v118, v118
	v_exp_f32_e32 v119, v119
	v_exp_f32_e32 v108, v108
	v_exp_f32_e32 v109, v109
	v_exp_f32_e32 v110, v110
	v_exp_f32_e32 v111, v111
	v_exp_f32_e32 v100, v100
	v_exp_f32_e32 v101, v101
	v_exp_f32_e32 v102, v102
	v_exp_f32_e32 v103, v103
	v_add_f32_e32 v156, 1.0, v156
	v_add_f32_e32 v157, 1.0, v157
	v_add_f32_e32 v158, 1.0, v158
	v_add_f32_e32 v159, 1.0, v159
	v_add_f32_e32 v116, 1.0, v116
	v_add_f32_e32 v117, 1.0, v117
	v_add_f32_e32 v118, 1.0, v118
	v_add_f32_e32 v119, 1.0, v119
	v_add_f32_e32 v108, 1.0, v108
	v_add_f32_e32 v109, 1.0, v109
	v_add_f32_e32 v110, 1.0, v110
	v_add_f32_e32 v111, 1.0, v111
	v_add_f32_e32 v100, 1.0, v100
	v_add_f32_e32 v101, 1.0, v101
	v_add_f32_e32 v102, 1.0, v102
	v_add_f32_e32 v103, 1.0, v103
	v_rcp_f32_e32 v156, v156
	v_rcp_f32_e32 v157, v157
	v_rcp_f32_e32 v158, v158
	v_rcp_f32_e32 v159, v159
	v_rcp_f32_e32 v116, v116
	v_rcp_f32_e32 v117, v117
	v_rcp_f32_e32 v118, v118
	v_rcp_f32_e32 v119, v119
	v_rcp_f32_e32 v108, v108
	v_rcp_f32_e32 v109, v109
	v_rcp_f32_e32 v110, v110
	v_rcp_f32_e32 v111, v111
	v_rcp_f32_e32 v100, v100
	v_rcp_f32_e32 v101, v101
	v_rcp_f32_e32 v102, v102
	v_rcp_f32_e32 v103, v103
	v_pk_mul_f32 v[176:177], v[176:177], v[156:157]
	v_pk_mul_f32 v[178:179], v[178:179], v[158:159]
	v_pk_mul_f32 v[180:181], v[180:181], v[116:117]
	v_pk_mul_f32 v[182:183], v[182:183], v[118:119]
	v_pk_mul_f32 v[184:185], v[184:185], v[108:109]
	v_pk_mul_f32 v[186:187], v[186:187], v[110:111]
	v_pk_mul_f32 v[224:225], v[224:225], v[100:101]
	v_pk_mul_f32 v[226:227], v[226:227], v[102:103]
	v_pk_mul_f32 v[176:177], v[152:153], v[176:177]
	v_pk_mul_f32 v[178:179], v[154:155], v[178:179]
	v_pk_mul_f32 v[180:181], v[112:113], v[180:181]
	v_pk_mul_f32 v[182:183], v[114:115], v[182:183]
	v_pk_mul_f32 v[184:185], v[104:105], v[184:185]
	v_pk_mul_f32 v[186:187], v[106:107], v[186:187]
	v_pk_mul_f32 v[224:225], v[96:97], v[224:225]
	v_pk_mul_f32 v[226:227], v[98:99], v[226:227]
	v_cvt_pk_bf16_f32 v156, v176, v177
	v_cvt_pk_bf16_f32 v157, v178, v179
	v_cvt_pk_bf16_f32 v116, v180, v181
	v_cvt_pk_bf16_f32 v117, v182, v183
	v_cvt_pk_bf16_f32 v108, v184, v185
	v_cvt_pk_bf16_f32 v109, v186, v187
	v_cvt_pk_bf16_f32 v100, v224, v225
	v_cvt_pk_bf16_f32 v101, v226, v227
	global_store_dwordx2 v173, v[156:157], s[0:1]
	v_add_u32_e32 v175, 0x2c00, v173
	global_store_dwordx2 v175, v[116:117], s[0:1]
	v_add_u32_e32 v175, 0x5800, v173
	global_store_dwordx2 v175, v[108:109], s[0:1]
	v_add_u32_e32 v175, 0x8400, v173
	global_store_dwordx2 v175, v[100:101], s[0:1]
	v_mov_b32_dpp v216, v64 row_shr:1 row_mask:0xf bank_mask:0xf bound_ctrl:1
	v_mov_b32_dpp v217, v65 row_shr:1 row_mask:0xf bank_mask:0xf bound_ctrl:1
	v_mov_b32_dpp v218, v66 row_shr:1 row_mask:0xf bank_mask:0xf bound_ctrl:1
	v_mov_b32_dpp v219, v67 row_shr:1 row_mask:0xf bank_mask:0xf bound_ctrl:1
	v_mov_b32_dpp v220, v88 row_shl:1 row_mask:0xf bank_mask:0xf bound_ctrl:1
	v_mov_b32_dpp v221, v89 row_shl:1 row_mask:0xf bank_mask:0xf bound_ctrl:1
	v_mov_b32_dpp v222, v90 row_shl:1 row_mask:0xf bank_mask:0xf bound_ctrl:1
	v_mov_b32_dpp v223, v91 row_shl:1 row_mask:0xf bank_mask:0xf bound_ctrl:1
	v_pk_mul_f32 v[176:177], v[88:89], v[140:141]
	v_pk_mul_f32 v[178:179], v[90:91], v[142:143]
	v_pk_mul_f32 v[180:181], v[80:81], v[140:141]
	v_pk_mul_f32 v[182:183], v[82:83], v[142:143]
	v_pk_mul_f32 v[184:185], v[72:73], v[140:141]
	v_pk_mul_f32 v[186:187], v[74:75], v[142:143]
	v_pk_mul_f32 v[224:225], v[64:65], v[140:141]
	v_pk_mul_f32 v[226:227], v[66:67], v[142:143]
	v_pk_fma_f32 v[176:177], v[136:137], v[216:217], v[176:177]
	v_pk_fma_f32 v[178:179], v[138:139], v[218:219], v[178:179]
	v_pk_fma_f32 v[180:181], v[136:137], v[88:89], v[180:181]
	v_pk_fma_f32 v[182:183], v[138:139], v[90:91], v[182:183]
	v_pk_fma_f32 v[184:185], v[136:137], v[80:81], v[184:185]
	v_pk_fma_f32 v[186:187], v[138:139], v[82:83], v[186:187]
	v_pk_fma_f32 v[224:225], v[136:137], v[72:73], v[224:225]
	v_pk_fma_f32 v[226:227], v[138:139], v[74:75], v[226:227]
	v_pk_fma_f32 v[176:177], v[144:145], v[80:81], v[176:177]
	v_pk_fma_f32 v[178:179], v[146:147], v[82:83], v[178:179]
	v_pk_fma_f32 v[180:181], v[144:145], v[72:73], v[180:181]
	v_pk_fma_f32 v[182:183], v[146:147], v[74:75], v[182:183]
	v_pk_fma_f32 v[184:185], v[144:145], v[64:65], v[184:185]
	v_pk_fma_f32 v[186:187], v[146:147], v[66:67], v[186:187]
	v_pk_fma_f32 v[224:225], v[144:145], v[220:221], v[224:225]
	v_pk_fma_f32 v[226:227], v[146:147], v[222:223], v[226:227]
	v_pk_add_f32 v[176:177], v[148:149], v[176:177]
	v_pk_add_f32 v[178:179], v[150:151], v[178:179]
; __device__ __forceinline__ void st_bf4(bf16_t* p, f32x4 v) { u32x2 w; w.x = pk2(v[0], v[1]); w.y = pk2(v[2], v[3]); *(u32x2*)p = w; }
; __device__ __forceinline__ float sigmoidf_(float x) { return __builtin_amdgcn_rcpf(1.f + __expf(-x)); }
; __device__ __forceinline__ float dpp_ror1(float v) { return __int_as_float(__builtin_amdgcn_update_dpp(0, __float_as_int(v), 0x121, 0xf, 0xf, false)); }
; __device__ __forceinline__ float dpp_rol1(float v) { return __int_as_float(__builtin_amdgcn_update_dpp(0, __float_as_int(v), 0x12F, 0xf, 0xf, false)); }
;     __device__ __forceinline__ void tile(const f32x4 (&acc)[2][2][4][2], const Unit& u, int wr, int wc, int fr, int fq) const {
;     ...
;                         const float xv = acc[ai][0][m][n][i], xg = acc[ai][1][m][n][i];
;                         const float uv = m > 0 ? acc[ai][0][m > 0 ? m - 1 : 0][n][i] : 0.f, ug = m > 0 ? acc[ai][1][m > 0 ? m - 1 : 0][n][i] : 0.f;
;                         const float dv = m < 3 ? acc[ai][0][m < 3 ? m + 1 : 3][n][i] : 0.f, dg = m < 3 ? acc[ai][1][m < 3 ? m + 1 : 3][n][i] : 0.f;
;                         const float pv = dpp_ror1(fr == 15 ? uv : xv), pg = dpp_ror1(fr == 15 ? ug : xg);
;                         const float nv = dpp_rol1(fr == 0 ? dv : xv), ng = dpp_rol1(fr == 0 ? dg : xg);
;                         const float yv = wv0[i] * pv + wv1[i] * xv + wv2[i] * nv + bv[i];
;                         const float yg = wg0[i] * pg + wg1[i] * xg + wg2[i] * ng + bg[i];
;                         r[i] = yg * sigmoidf_(yg) * yv;
;                     }
;                     st_bf4(ACT + (size_t)(u.pm * BM + ai * HALF + wr * 64 + m * 16 + fr) * FF + cv, r);
	v_pk_add_f32 v[180:181], v[148:149], v[180:181]
	v_pk_add_f32 v[182:183], v[150:151], v[182:183]
	v_pk_add_f32 v[184:185], v[148:149], v[184:185]
	v_pk_add_f32 v[186:187], v[150:151], v[186:187]
	v_pk_add_f32 v[224:225], v[148:149], v[224:225]
	v_pk_add_f32 v[226:227], v[150:151], v[226:227]
	v_mov_b32_dpp v216, v68 row_shr:1 row_mask:0xf bank_mask:0xf bound_ctrl:1
	v_mov_b32_dpp v217, v69 row_shr:1 row_mask:0xf bank_mask:0xf bound_ctrl:1
	v_mov_b32_dpp v218, v70 row_shr:1 row_mask:0xf bank_mask:0xf bound_ctrl:1
	v_mov_b32_dpp v219, v71 row_shr:1 row_mask:0xf bank_mask:0xf bound_ctrl:1
	v_mov_b32_dpp v220, v92 row_shl:1 row_mask:0xf bank_mask:0xf bound_ctrl:1
	v_mov_b32_dpp v221, v93 row_shl:1 row_mask:0xf bank_mask:0xf bound_ctrl:1
	v_mov_b32_dpp v222, v94 row_shl:1 row_mask:0xf bank_mask:0xf bound_ctrl:1
	v_mov_b32_dpp v223, v95 row_shl:1 row_mask:0xf bank_mask:0xf bound_ctrl:1
	v_pk_mul_f32 v[88:89], v[92:93], v[124:125]
	v_pk_mul_f32 v[90:91], v[94:95], v[126:127]
	v_pk_mul_f32 v[80:81], v[84:85], v[124:125]
	v_pk_mul_f32 v[82:83], v[86:87], v[126:127]
	v_pk_mul_f32 v[72:73], v[76:77], v[124:125]
	v_pk_mul_f32 v[74:75], v[78:79], v[126:127]
	v_pk_mul_f32 v[64:65], v[68:69], v[124:125]
	v_pk_mul_f32 v[66:67], v[70:71], v[126:127]
	v_pk_fma_f32 v[88:89], v[120:121], v[216:217], v[88:89]
	v_pk_fma_f32 v[90:91], v[122:123], v[218:219], v[90:91]
	v_pk_fma_f32 v[80:81], v[120:121], v[92:93], v[80:81]
	v_pk_fma_f32 v[82:83], v[122:123], v[94:95], v[82:83]
	v_pk_fma_f32 v[72:73], v[120:121], v[84:85], v[72:73]
	v_pk_fma_f32 v[74:75], v[122:123], v[86:87], v[74:75]
	v_pk_fma_f32 v[64:65], v[120:121], v[76:77], v[64:65]
	v_pk_fma_f32 v[66:67], v[122:123], v[78:79], v[66:67]
	v_pk_fma_f32 v[88:89], v[128:129], v[84:85], v[88:89]
	v_pk_fma_f32 v[90:91], v[130:131], v[86:87], v[90:91]
	v_pk_fma_f32 v[80:81], v[128:129], v[76:77], v[80:81]
	v_pk_fma_f32 v[82:83], v[130:131], v[78:79], v[82:83]
	v_pk_fma_f32 v[72:73], v[128:129], v[68:69], v[72:73]
	v_pk_fma_f32 v[74:75], v[130:131], v[70:71], v[74:75]
	v_pk_fma_f32 v[64:65], v[128:129], v[220:221], v[64:65]
	v_pk_fma_f32 v[66:67], v[130:131], v[222:223], v[66:67]
	v_pk_add_f32 v[88:89], v[132:133], v[88:89]
	v_pk_add_f32 v[90:91], v[134:135], v[90:91]
	v_pk_add_f32 v[80:81], v[132:133], v[80:81]
	v_pk_add_f32 v[82:83], v[134:135], v[82:83]
	v_pk_add_f32 v[72:73], v[132:133], v[72:73]
	v_pk_add_f32 v[74:75], v[134:135], v[74:75]
	v_pk_add_f32 v[64:65], v[132:133], v[64:65]
	v_pk_add_f32 v[66:67], v[134:135], v[66:67]
	v_mul_f32_e32 v92, 0xbfb8aa3b, v176
	v_mul_f32_e32 v93, 0xbfb8aa3b, v177
	v_mul_f32_e32 v94, 0xbfb8aa3b, v178
	v_mul_f32_e32 v95, 0xbfb8aa3b, v179
	v_mul_f32_e32 v84, 0xbfb8aa3b, v180
	v_mul_f32_e32 v85, 0xbfb8aa3b, v181
	v_mul_f32_e32 v86, 0xbfb8aa3b, v182
	v_mul_f32_e32 v87, 0xbfb8aa3b, v183
	v_mul_f32_e32 v76, 0xbfb8aa3b, v184
	v_mul_f32_e32 v77, 0xbfb8aa3b, v185
	v_mul_f32_e32 v78, 0xbfb8aa3b, v186
	v_mul_f32_e32 v79, 0xbfb8aa3b, v187
	v_mul_f32_e32 v68, 0xbfb8aa3b, v224
	v_mul_f32_e32 v69, 0xbfb8aa3b, v225
	v_mul_f32_e32 v70, 0xbfb8aa3b, v226
	v_mul_f32_e32 v71, 0xbfb8aa3b, v227
	v_exp_f32_e32 v92, v92
	v_exp_f32_e32 v93, v93
	v_exp_f32_e32 v94, v94
	v_exp_f32_e32 v95, v95
	v_exp_f32_e32 v84, v84
	v_exp_f32_e32 v85, v85
	v_exp_f32_e32 v86, v86
	v_exp_f32_e32 v87, v87
	v_exp_f32_e32 v76, v76
	v_exp_f32_e32 v77, v77
	v_exp_f32_e32 v78, v78
	v_exp_f32_e32 v79, v79
	v_exp_f32_e32 v68, v68
	v_exp_f32_e32 v69, v69
	v_exp_f32_e32 v70, v70
	v_exp_f32_e32 v71, v71
	v_add_f32_e32 v92, 1.0, v92
	v_add_f32_e32 v93, 1.0, v93
	v_add_f32_e32 v94, 1.0, v94
	v_add_f32_e32 v95, 1.0, v95
	v_add_f32_e32 v84, 1.0, v84
	v_add_f32_e32 v85, 1.0, v85
	v_add_f32_e32 v86, 1.0, v86
	v_add_f32_e32 v87, 1.0, v87
	v_add_f32_e32 v76, 1.0, v76
	v_add_f32_e32 v77, 1.0, v77
	v_add_f32_e32 v78, 1.0, v78
	v_add_f32_e32 v79, 1.0, v79
	v_add_f32_e32 v68, 1.0, v68
	v_add_f32_e32 v69, 1.0, v69
	v_add_f32_e32 v70, 1.0, v70
	v_add_f32_e32 v71, 1.0, v71
	v_rcp_f32_e32 v92, v92
	v_rcp_f32_e32 v93, v93
	v_rcp_f32_e32 v94, v94
	v_rcp_f32_e32 v95, v95
	v_rcp_f32_e32 v84, v84
	v_rcp_f32_e32 v85, v85
	v_rcp_f32_e32 v86, v86
	v_rcp_f32_e32 v87, v87
	v_rcp_f32_e32 v76, v76
	v_rcp_f32_e32 v77, v77
	v_rcp_f32_e32 v78, v78
	v_rcp_f32_e32 v79, v79
	v_rcp_f32_e32 v68, v68
	v_rcp_f32_e32 v69, v69
	v_rcp_f32_e32 v70, v70
	v_rcp_f32_e32 v71, v71
	v_pk_mul_f32 v[176:177], v[176:177], v[92:93]
	v_pk_mul_f32 v[178:179], v[178:179], v[94:95]
	v_pk_mul_f32 v[180:181], v[180:181], v[84:85]
	v_pk_mul_f32 v[182:183], v[182:183], v[86:87]
	v_pk_mul_f32 v[184:185], v[184:185], v[76:77]
	v_pk_mul_f32 v[186:187], v[186:187], v[78:79]
	v_pk_mul_f32 v[224:225], v[224:225], v[68:69]
	v_pk_mul_f32 v[226:227], v[226:227], v[70:71]
	v_pk_mul_f32 v[176:177], v[88:89], v[176:177]
	v_pk_mul_f32 v[178:179], v[90:91], v[178:179]
	v_pk_mul_f32 v[180:181], v[80:81], v[180:181]
	v_pk_mul_f32 v[182:183], v[82:83], v[182:183]
	v_pk_mul_f32 v[184:185], v[72:73], v[184:185]
	v_pk_mul_f32 v[186:187], v[74:75], v[186:187]
	v_pk_mul_f32 v[224:225], v[64:65], v[224:225]
	v_pk_mul_f32 v[226:227], v[66:67], v[226:227]
	v_cvt_pk_bf16_f32 v92, v176, v177
	v_cvt_pk_bf16_f32 v93, v178, v179
	v_cvt_pk_bf16_f32 v84, v180, v181
	v_cvt_pk_bf16_f32 v85, v182, v183
	v_cvt_pk_bf16_f32 v76, v184, v185
	v_cvt_pk_bf16_f32 v77, v186, v187
	v_cvt_pk_bf16_f32 v68, v224, v225
	v_cvt_pk_bf16_f32 v69, v226, v227
	global_store_dwordx2 v174, v[92:93], s[0:1]
	v_add_u32_e32 v175, 0x2c00, v174
	global_store_dwordx2 v175, v[84:85], s[0:1]
	v_add_u32_e32 v175, 0x5800, v174
	global_store_dwordx2 v175, v[76:77], s[0:1]
	v_add_u32_e32 v175, 0x8400, v174
	global_store_dwordx2 v175, v[68:69], s[0:1]
	s_waitcnt vmcnt(12)
; __device__ __forceinline__ float sigmoidf_(float x) { return __builtin_amdgcn_rcpf(1.f + __expf(-x)); }
; __device__ __forceinline__ float dpp_ror1(float v) { return __int_as_float(__builtin_amdgcn_update_dpp(0, __float_as_int(v), 0x121, 0xf, 0xf, false)); }
; __device__ __forceinline__ float dpp_rol1(float v) { return __int_as_float(__builtin_amdgcn_update_dpp(0, __float_as_int(v), 0x12F, 0xf, 0xf, false)); }
;     __device__ __forceinline__ void tile(const f32x4 (&acc)[2][2][4][2], const Unit& u, int wr, int wc, int fr, int fq) const {
;     ...
;                     for (int i = 0; i < 4; ++i) {
;                         const float xv = acc[ai][0][m][n][i], xg = acc[ai][1][m][n][i];
;                         const float uv = m > 0 ? acc[ai][0][m > 0 ? m - 1 : 0][n][i] : 0.f, ug = m > 0 ? acc[ai][1][m > 0 ? m - 1 : 0][n][i] : 0.f;
;                         const float dv = m < 3 ? acc[ai][0][m < 3 ? m + 1 : 3][n][i] : 0.f, dg = m < 3 ? acc[ai][1][m < 3 ? m + 1 : 3][n][i] : 0.f;
;                         const float pv = dpp_ror1(fr == 15 ? uv : xv), pg = dpp_ror1(fr == 15 ? ug : xg);
;                         const float nv = dpp_rol1(fr == 0 ? dv : xv), ng = dpp_rol1(fr == 0 ? dg : xg);
;                         const float yv = wv0[i] * pv + wv1[i] * xv + wv2[i] * nv + bv[i];
;                         const float yg = wg0[i] * pg + wg1[i] * xg + wg2[i] * ng + bg[i];
;                         r[i] = yg * sigmoidf_(yg) * yv;
	v_mov_b32_dpp v216, v32 row_shr:1 row_mask:0xf bank_mask:0xf bound_ctrl:1
	v_mov_b32_dpp v217, v33 row_shr:1 row_mask:0xf bank_mask:0xf bound_ctrl:1
	v_mov_b32_dpp v218, v34 row_shr:1 row_mask:0xf bank_mask:0xf bound_ctrl:1
	v_mov_b32_dpp v219, v35 row_shr:1 row_mask:0xf bank_mask:0xf bound_ctrl:1
	v_mov_b32_dpp v220, v56 row_shl:1 row_mask:0xf bank_mask:0xf bound_ctrl:1
	v_mov_b32_dpp v221, v57 row_shl:1 row_mask:0xf bank_mask:0xf bound_ctrl:1
	v_mov_b32_dpp v222, v58 row_shl:1 row_mask:0xf bank_mask:0xf bound_ctrl:1
	v_mov_b32_dpp v223, v59 row_shl:1 row_mask:0xf bank_mask:0xf bound_ctrl:1
	v_pk_mul_f32 v[176:177], v[56:57], v[250:251]
	v_pk_mul_f32 v[178:179], v[58:59], v[252:253]
	v_pk_mul_f32 v[180:181], v[48:49], v[250:251]
	v_pk_mul_f32 v[182:183], v[50:51], v[252:253]
	v_pk_mul_f32 v[184:185], v[40:41], v[250:251]
	v_pk_mul_f32 v[186:187], v[42:43], v[252:253]
	v_pk_mul_f32 v[224:225], v[32:33], v[250:251]
	v_pk_mul_f32 v[226:227], v[34:35], v[252:253]
	v_pk_fma_f32 v[176:177], v[246:247], v[216:217], v[176:177]
	v_pk_fma_f32 v[178:179], v[248:249], v[218:219], v[178:179]
	v_pk_fma_f32 v[180:181], v[246:247], v[56:57], v[180:181]
	v_pk_fma_f32 v[182:183], v[248:249], v[58:59], v[182:183]
	v_pk_fma_f32 v[184:185], v[246:247], v[48:49], v[184:185]
	v_pk_fma_f32 v[186:187], v[248:249], v[50:51], v[186:187]
	v_pk_fma_f32 v[224:225], v[246:247], v[40:41], v[224:225]
	v_pk_fma_f32 v[226:227], v[248:249], v[42:43], v[226:227]
	v_pk_fma_f32 v[176:177], v[208:209], v[48:49], v[176:177]
	v_pk_fma_f32 v[178:179], v[210:211], v[50:51], v[178:179]
	v_pk_fma_f32 v[180:181], v[208:209], v[40:41], v[180:181]
	v_pk_fma_f32 v[182:183], v[210:211], v[42:43], v[182:183]
	v_pk_fma_f32 v[184:185], v[208:209], v[32:33], v[184:185]
	v_pk_fma_f32 v[186:187], v[210:211], v[34:35], v[186:187]
	v_pk_fma_f32 v[224:225], v[208:209], v[220:221], v[224:225]
	v_pk_fma_f32 v[226:227], v[210:211], v[222:223], v[226:227]
	v_pk_add_f32 v[176:177], v[212:213], v[176:177]
	v_pk_add_f32 v[178:179], v[214:215], v[178:179]
	v_pk_add_f32 v[180:181], v[212:213], v[180:181]
	v_pk_add_f32 v[182:183], v[214:215], v[182:183]
	v_pk_add_f32 v[184:185], v[212:213], v[184:185]
	v_pk_add_f32 v[186:187], v[214:215], v[186:187]
	v_pk_add_f32 v[224:225], v[212:213], v[224:225]
	v_pk_add_f32 v[226:227], v[214:215], v[226:227]
	s_waitcnt vmcnt(8)
	v_mov_b32_dpp v216, v36 row_shr:1 row_mask:0xf bank_mask:0xf bound_ctrl:1
	v_mov_b32_dpp v217, v37 row_shr:1 row_mask:0xf bank_mask:0xf bound_ctrl:1
	v_mov_b32_dpp v218, v38 row_shr:1 row_mask:0xf bank_mask:0xf bound_ctrl:1
	v_mov_b32_dpp v219, v39 row_shr:1 row_mask:0xf bank_mask:0xf bound_ctrl:1
	v_mov_b32_dpp v220, v60 row_shl:1 row_mask:0xf bank_mask:0xf bound_ctrl:1
	v_mov_b32_dpp v221, v61 row_shl:1 row_mask:0xf bank_mask:0xf bound_ctrl:1
	v_mov_b32_dpp v222, v62 row_shl:1 row_mask:0xf bank_mask:0xf bound_ctrl:1
	v_mov_b32_dpp v223, v63 row_shl:1 row_mask:0xf bank_mask:0xf bound_ctrl:1
	v_pk_mul_f32 v[56:57], v[60:61], v[234:235]
	v_pk_mul_f32 v[58:59], v[62:63], v[236:237]
	v_pk_mul_f32 v[48:49], v[52:53], v[234:235]
	v_pk_mul_f32 v[50:51], v[54:55], v[236:237]
	v_pk_mul_f32 v[40:41], v[44:45], v[234:235]
	v_pk_mul_f32 v[42:43], v[46:47], v[236:237]
	v_pk_mul_f32 v[32:33], v[36:37], v[234:235]
	v_pk_mul_f32 v[34:35], v[38:39], v[236:237]
	v_pk_fma_f32 v[56:57], v[230:231], v[216:217], v[56:57]
	v_pk_fma_f32 v[58:59], v[232:233], v[218:219], v[58:59]
	v_pk_fma_f32 v[48:49], v[230:231], v[60:61], v[48:49]
	v_pk_fma_f32 v[50:51], v[232:233], v[62:63], v[50:51]
	v_pk_fma_f32 v[40:41], v[230:231], v[52:53], v[40:41]
	v_pk_fma_f32 v[42:43], v[232:233], v[54:55], v[42:43]
	v_pk_fma_f32 v[32:33], v[230:231], v[44:45], v[32:33]
	v_pk_fma_f32 v[34:35], v[232:233], v[46:47], v[34:35]
	v_pk_fma_f32 v[56:57], v[238:239], v[52:53], v[56:57]
	v_pk_fma_f32 v[58:59], v[240:241], v[54:55], v[58:59]
	v_pk_fma_f32 v[48:49], v[238:239], v[44:45], v[48:49]
	v_pk_fma_f32 v[50:51], v[240:241], v[46:47], v[50:51]
	v_pk_fma_f32 v[40:41], v[238:239], v[36:37], v[40:41]
	v_pk_fma_f32 v[42:43], v[240:241], v[38:39], v[42:43]
	v_pk_fma_f32 v[32:33], v[238:239], v[220:221], v[32:33]
	v_pk_fma_f32 v[34:35], v[240:241], v[222:223], v[34:35]
	v_pk_add_f32 v[56:57], v[242:243], v[56:57]
	v_pk_add_f32 v[58:59], v[244:245], v[58:59]
	v_pk_add_f32 v[48:49], v[242:243], v[48:49]
	v_pk_add_f32 v[50:51], v[244:245], v[50:51]
	v_pk_add_f32 v[40:41], v[242:243], v[40:41]
	v_pk_add_f32 v[42:43], v[244:245], v[42:43]
	v_pk_add_f32 v[32:33], v[242:243], v[32:33]
	v_pk_add_f32 v[34:35], v[244:245], v[34:35]
	v_mul_f32_e32 v60, 0xbfb8aa3b, v176
	v_mul_f32_e32 v61, 0xbfb8aa3b, v177
	v_mul_f32_e32 v62, 0xbfb8aa3b, v178
	v_mul_f32_e32 v63, 0xbfb8aa3b, v179
	v_mul_f32_e32 v52, 0xbfb8aa3b, v180
	v_mul_f32_e32 v53, 0xbfb8aa3b, v181
	v_mul_f32_e32 v54, 0xbfb8aa3b, v182
	v_mul_f32_e32 v55, 0xbfb8aa3b, v183
	v_mul_f32_e32 v44, 0xbfb8aa3b, v184
	v_mul_f32_e32 v45, 0xbfb8aa3b, v185
	v_mul_f32_e32 v46, 0xbfb8aa3b, v186
	v_mul_f32_e32 v47, 0xbfb8aa3b, v187
	v_mul_f32_e32 v36, 0xbfb8aa3b, v224
	v_mul_f32_e32 v37, 0xbfb8aa3b, v225
	v_mul_f32_e32 v38, 0xbfb8aa3b, v226
	v_mul_f32_e32 v39, 0xbfb8aa3b, v227
	v_exp_f32_e32 v60, v60
	v_exp_f32_e32 v61, v61
	v_exp_f32_e32 v62, v62
	v_exp_f32_e32 v63, v63
	v_exp_f32_e32 v52, v52
	v_exp_f32_e32 v53, v53
	v_exp_f32_e32 v54, v54
	v_exp_f32_e32 v55, v55
	v_exp_f32_e32 v44, v44
	v_exp_f32_e32 v45, v45
	v_exp_f32_e32 v46, v46
	v_exp_f32_e32 v47, v47
	v_exp_f32_e32 v36, v36
	v_exp_f32_e32 v37, v37
	v_exp_f32_e32 v38, v38
	v_exp_f32_e32 v39, v39
	v_add_f32_e32 v60, 1.0, v60
	v_add_f32_e32 v61, 1.0, v61
	v_add_f32_e32 v62, 1.0, v62
	v_add_f32_e32 v63, 1.0, v63
; __device__ __forceinline__ void st_bf4(bf16_t* p, f32x4 v) { u32x2 w; w.x = pk2(v[0], v[1]); w.y = pk2(v[2], v[3]); *(u32x2*)p = w; }
; __device__ __forceinline__ float sigmoidf_(float x) { return __builtin_amdgcn_rcpf(1.f + __expf(-x)); }
; __device__ __forceinline__ float dpp_ror1(float v) { return __int_as_float(__builtin_amdgcn_update_dpp(0, __float_as_int(v), 0x121, 0xf, 0xf, false)); }
; __device__ __forceinline__ float dpp_rol1(float v) { return __int_as_float(__builtin_amdgcn_update_dpp(0, __float_as_int(v), 0x12F, 0xf, 0xf, false)); }
;     __device__ __forceinline__ void tile(const f32x4 (&acc)[2][2][4][2], const Unit& u, int wr, int wc, int fr, int fq) const {
;     ...
;                     for (int i = 0; i < 4; ++i) {
;                         const float xv = acc[ai][0][m][n][i], xg = acc[ai][1][m][n][i];
;                         const float uv = m > 0 ? acc[ai][0][m > 0 ? m - 1 : 0][n][i] : 0.f, ug = m > 0 ? acc[ai][1][m > 0 ? m - 1 : 0][n][i] : 0.f;
;                         const float dv = m < 3 ? acc[ai][0][m < 3 ? m + 1 : 3][n][i] : 0.f, dg = m < 3 ? acc[ai][1][m < 3 ? m + 1 : 3][n][i] : 0.f;
;                         const float pv = dpp_ror1(fr == 15 ? uv : xv), pg = dpp_ror1(fr == 15 ? ug : xg);
;                         const float nv = dpp_rol1(fr == 0 ? dv : xv), ng = dpp_rol1(fr == 0 ? dg : xg);
;                         const float yv = wv0[i] * pv + wv1[i] * xv + wv2[i] * nv + bv[i];
;                         const float yg = wg0[i] * pg + wg1[i] * xg + wg2[i] * ng + bg[i];
;                         r[i] = yg * sigmoidf_(yg) * yv;
;                     }
;                     st_bf4(ACT + (size_t)(u.pm * BM + ai * HALF + wr * 64 + m * 16 + fr) * FF + cv, r);
	v_add_f32_e32 v52, 1.0, v52
	v_add_f32_e32 v53, 1.0, v53
	v_add_f32_e32 v54, 1.0, v54
	v_add_f32_e32 v55, 1.0, v55
	v_add_f32_e32 v44, 1.0, v44
	v_add_f32_e32 v45, 1.0, v45
	v_add_f32_e32 v46, 1.0, v46
	v_add_f32_e32 v47, 1.0, v47
	v_add_f32_e32 v36, 1.0, v36
	v_add_f32_e32 v37, 1.0, v37
	v_add_f32_e32 v38, 1.0, v38
	v_add_f32_e32 v39, 1.0, v39
	v_rcp_f32_e32 v60, v60
	v_rcp_f32_e32 v61, v61
	v_rcp_f32_e32 v62, v62
	v_rcp_f32_e32 v63, v63
	v_rcp_f32_e32 v52, v52
	v_rcp_f32_e32 v53, v53
	v_rcp_f32_e32 v54, v54
	v_rcp_f32_e32 v55, v55
	v_rcp_f32_e32 v44, v44
	v_rcp_f32_e32 v45, v45
	v_rcp_f32_e32 v46, v46
	v_rcp_f32_e32 v47, v47
	v_rcp_f32_e32 v36, v36
	v_rcp_f32_e32 v37, v37
	v_rcp_f32_e32 v38, v38
	v_rcp_f32_e32 v39, v39
	v_pk_mul_f32 v[176:177], v[176:177], v[60:61]
	v_pk_mul_f32 v[178:179], v[178:179], v[62:63]
	v_pk_mul_f32 v[180:181], v[180:181], v[52:53]
	v_pk_mul_f32 v[182:183], v[182:183], v[54:55]
	v_pk_mul_f32 v[184:185], v[184:185], v[44:45]
	v_pk_mul_f32 v[186:187], v[186:187], v[46:47]
	v_pk_mul_f32 v[224:225], v[224:225], v[36:37]
	v_pk_mul_f32 v[226:227], v[226:227], v[38:39]
	v_pk_mul_f32 v[176:177], v[56:57], v[176:177]
	v_pk_mul_f32 v[178:179], v[58:59], v[178:179]
	v_pk_mul_f32 v[180:181], v[48:49], v[180:181]
	v_pk_mul_f32 v[182:183], v[50:51], v[182:183]
	v_pk_mul_f32 v[184:185], v[40:41], v[184:185]
	v_pk_mul_f32 v[186:187], v[42:43], v[186:187]
	v_pk_mul_f32 v[224:225], v[32:33], v[224:225]
	v_pk_mul_f32 v[226:227], v[34:35], v[226:227]
	v_cvt_pk_bf16_f32 v60, v176, v177
	v_cvt_pk_bf16_f32 v61, v178, v179
	v_cvt_pk_bf16_f32 v52, v180, v181
	v_cvt_pk_bf16_f32 v53, v182, v183
	v_cvt_pk_bf16_f32 v44, v184, v185
	v_cvt_pk_bf16_f32 v45, v186, v187
	v_cvt_pk_bf16_f32 v36, v224, v225
	v_cvt_pk_bf16_f32 v37, v226, v227
	global_store_dwordx2 v173, v[60:61], s[0:1] offset:32
	v_add_u32_e32 v175, 0x2c00, v173
	global_store_dwordx2 v175, v[52:53], s[0:1] offset:32
	v_add_u32_e32 v175, 0x5800, v173
	global_store_dwordx2 v175, v[44:45], s[0:1] offset:32
	v_add_u32_e32 v175, 0x8400, v173
	global_store_dwordx2 v175, v[36:37], s[0:1] offset:32
	v_mov_b32_dpp v216, v0 row_shr:1 row_mask:0xf bank_mask:0xf bound_ctrl:1
	v_mov_b32_dpp v217, v1 row_shr:1 row_mask:0xf bank_mask:0xf bound_ctrl:1
	v_mov_b32_dpp v218, v2 row_shr:1 row_mask:0xf bank_mask:0xf bound_ctrl:1
	v_mov_b32_dpp v219, v3 row_shr:1 row_mask:0xf bank_mask:0xf bound_ctrl:1
	v_mov_b32_dpp v220, v24 row_shl:1 row_mask:0xf bank_mask:0xf bound_ctrl:1
	v_mov_b32_dpp v221, v25 row_shl:1 row_mask:0xf bank_mask:0xf bound_ctrl:1
	v_mov_b32_dpp v222, v26 row_shl:1 row_mask:0xf bank_mask:0xf bound_ctrl:1
	v_mov_b32_dpp v223, v27 row_shl:1 row_mask:0xf bank_mask:0xf bound_ctrl:1
	v_pk_mul_f32 v[176:177], v[24:25], v[250:251]
	v_pk_mul_f32 v[178:179], v[26:27], v[252:253]
	v_pk_mul_f32 v[180:181], v[16:17], v[250:251]
	v_pk_mul_f32 v[182:183], v[18:19], v[252:253]
	v_pk_mul_f32 v[184:185], v[8:9], v[250:251]
	v_pk_mul_f32 v[186:187], v[10:11], v[252:253]
	v_pk_mul_f32 v[224:225], v[0:1], v[250:251]
	v_pk_mul_f32 v[226:227], v[2:3], v[252:253]
	v_pk_fma_f32 v[176:177], v[246:247], v[216:217], v[176:177]
	v_pk_fma_f32 v[178:179], v[248:249], v[218:219], v[178:179]
	v_pk_fma_f32 v[180:181], v[246:247], v[24:25], v[180:181]
	v_pk_fma_f32 v[182:183], v[248:249], v[26:27], v[182:183]
	v_pk_fma_f32 v[184:185], v[246:247], v[16:17], v[184:185]
	v_pk_fma_f32 v[186:187], v[248:249], v[18:19], v[186:187]
	v_pk_fma_f32 v[224:225], v[246:247], v[8:9], v[224:225]
	v_pk_fma_f32 v[226:227], v[248:249], v[10:11], v[226:227]
	v_pk_fma_f32 v[176:177], v[208:209], v[16:17], v[176:177]
	v_pk_fma_f32 v[178:179], v[210:211], v[18:19], v[178:179]
	v_pk_fma_f32 v[180:181], v[208:209], v[8:9], v[180:181]
	v_pk_fma_f32 v[182:183], v[210:211], v[10:11], v[182:183]
	v_pk_fma_f32 v[184:185], v[208:209], v[0:1], v[184:185]
	v_pk_fma_f32 v[186:187], v[210:211], v[2:3], v[186:187]
	v_pk_fma_f32 v[224:225], v[208:209], v[220:221], v[224:225]
	v_pk_fma_f32 v[226:227], v[210:211], v[222:223], v[226:227]
	v_pk_add_f32 v[176:177], v[212:213], v[176:177]
	v_pk_add_f32 v[178:179], v[214:215], v[178:179]
	v_pk_add_f32 v[180:181], v[212:213], v[180:181]
	v_pk_add_f32 v[182:183], v[214:215], v[182:183]
	v_pk_add_f32 v[184:185], v[212:213], v[184:185]
	v_pk_add_f32 v[186:187], v[214:215], v[186:187]
	v_pk_add_f32 v[224:225], v[212:213], v[224:225]
	v_pk_add_f32 v[226:227], v[214:215], v[226:227]
	v_mov_b32_dpp v216, v4 row_shr:1 row_mask:0xf bank_mask:0xf bound_ctrl:1
	v_mov_b32_dpp v217, v5 row_shr:1 row_mask:0xf bank_mask:0xf bound_ctrl:1
	v_mov_b32_dpp v218, v6 row_shr:1 row_mask:0xf bank_mask:0xf bound_ctrl:1
	v_mov_b32_dpp v219, v7 row_shr:1 row_mask:0xf bank_mask:0xf bound_ctrl:1
	v_mov_b32_dpp v220, v28 row_shl:1 row_mask:0xf bank_mask:0xf bound_ctrl:1
	v_mov_b32_dpp v221, v29 row_shl:1 row_mask:0xf bank_mask:0xf bound_ctrl:1
	v_mov_b32_dpp v222, v30 row_shl:1 row_mask:0xf bank_mask:0xf bound_ctrl:1
; __device__ __forceinline__ void st_bf4(bf16_t* p, f32x4 v) { u32x2 w; w.x = pk2(v[0], v[1]); w.y = pk2(v[2], v[3]); *(u32x2*)p = w; }
; __device__ __forceinline__ float sigmoidf_(float x) { return __builtin_amdgcn_rcpf(1.f + __expf(-x)); }
; __device__ __forceinline__ float dpp_ror1(float v) { return __int_as_float(__builtin_amdgcn_update_dpp(0, __float_as_int(v), 0x121, 0xf, 0xf, false)); }
; __device__ __forceinline__ float dpp_rol1(float v) { return __int_as_float(__builtin_amdgcn_update_dpp(0, __float_as_int(v), 0x12F, 0xf, 0xf, false)); }
;     __device__ __forceinline__ void tile(const f32x4 (&acc)[2][2][4][2], const Unit& u, int wr, int wc, int fr, int fq) const {
;     ...
;                     for (int i = 0; i < 4; ++i) {
;                         const float xv = acc[ai][0][m][n][i], xg = acc[ai][1][m][n][i];
;                         const float uv = m > 0 ? acc[ai][0][m > 0 ? m - 1 : 0][n][i] : 0.f, ug = m > 0 ? acc[ai][1][m > 0 ? m - 1 : 0][n][i] : 0.f;
;                         const float dv = m < 3 ? acc[ai][0][m < 3 ? m + 1 : 3][n][i] : 0.f, dg = m < 3 ? acc[ai][1][m < 3 ? m + 1 : 3][n][i] : 0.f;
;                         const float pv = dpp_ror1(fr == 15 ? uv : xv), pg = dpp_ror1(fr == 15 ? ug : xg);
;                         const float nv = dpp_rol1(fr == 0 ? dv : xv), ng = dpp_rol1(fr == 0 ? dg : xg);
;                         const float yv = wv0[i] * pv + wv1[i] * xv + wv2[i] * nv + bv[i];
;                         const float yg = wg0[i] * pg + wg1[i] * xg + wg2[i] * ng + bg[i];
;                         r[i] = yg * sigmoidf_(yg) * yv;
;                     }
;                     st_bf4(ACT + (size_t)(u.pm * BM + ai * HALF + wr * 64 + m * 16 + fr) * FF + cv, r);
	v_mov_b32_dpp v223, v31 row_shl:1 row_mask:0xf bank_mask:0xf bound_ctrl:1
	v_pk_mul_f32 v[24:25], v[28:29], v[234:235]
	v_pk_mul_f32 v[26:27], v[30:31], v[236:237]
	v_pk_mul_f32 v[16:17], v[20:21], v[234:235]
	v_pk_mul_f32 v[18:19], v[22:23], v[236:237]
	v_pk_mul_f32 v[8:9], v[12:13], v[234:235]
	v_pk_mul_f32 v[10:11], v[14:15], v[236:237]
	v_pk_mul_f32 v[0:1], v[4:5], v[234:235]
	v_pk_mul_f32 v[2:3], v[6:7], v[236:237]
	v_pk_fma_f32 v[24:25], v[230:231], v[216:217], v[24:25]
	v_pk_fma_f32 v[26:27], v[232:233], v[218:219], v[26:27]
	v_pk_fma_f32 v[16:17], v[230:231], v[28:29], v[16:17]
	v_pk_fma_f32 v[18:19], v[232:233], v[30:31], v[18:19]
	v_pk_fma_f32 v[8:9], v[230:231], v[20:21], v[8:9]
	v_pk_fma_f32 v[10:11], v[232:233], v[22:23], v[10:11]
	v_pk_fma_f32 v[0:1], v[230:231], v[12:13], v[0:1]
	v_pk_fma_f32 v[2:3], v[232:233], v[14:15], v[2:3]
	v_pk_fma_f32 v[24:25], v[238:239], v[20:21], v[24:25]
	v_pk_fma_f32 v[26:27], v[240:241], v[22:23], v[26:27]
	v_pk_fma_f32 v[16:17], v[238:239], v[12:13], v[16:17]
	v_pk_fma_f32 v[18:19], v[240:241], v[14:15], v[18:19]
	v_pk_fma_f32 v[8:9], v[238:239], v[4:5], v[8:9]
	v_pk_fma_f32 v[10:11], v[240:241], v[6:7], v[10:11]
	v_pk_fma_f32 v[0:1], v[238:239], v[220:221], v[0:1]
	v_pk_fma_f32 v[2:3], v[240:241], v[222:223], v[2:3]
	v_pk_add_f32 v[24:25], v[242:243], v[24:25]
	v_pk_add_f32 v[26:27], v[244:245], v[26:27]
	v_pk_add_f32 v[16:17], v[242:243], v[16:17]
	v_pk_add_f32 v[18:19], v[244:245], v[18:19]
	v_pk_add_f32 v[8:9], v[242:243], v[8:9]
	v_pk_add_f32 v[10:11], v[244:245], v[10:11]
	v_pk_add_f32 v[0:1], v[242:243], v[0:1]
	v_pk_add_f32 v[2:3], v[244:245], v[2:3]
	v_mul_f32_e32 v28, 0xbfb8aa3b, v176
	v_mul_f32_e32 v29, 0xbfb8aa3b, v177
	v_mul_f32_e32 v30, 0xbfb8aa3b, v178
	v_mul_f32_e32 v31, 0xbfb8aa3b, v179
	v_mul_f32_e32 v20, 0xbfb8aa3b, v180
	v_mul_f32_e32 v21, 0xbfb8aa3b, v181
	v_mul_f32_e32 v22, 0xbfb8aa3b, v182
	v_mul_f32_e32 v23, 0xbfb8aa3b, v183
	v_mul_f32_e32 v12, 0xbfb8aa3b, v184
	v_mul_f32_e32 v13, 0xbfb8aa3b, v185
	v_mul_f32_e32 v14, 0xbfb8aa3b, v186
	v_mul_f32_e32 v15, 0xbfb8aa3b, v187
	v_mul_f32_e32 v4, 0xbfb8aa3b, v224
	v_mul_f32_e32 v5, 0xbfb8aa3b, v225
	v_mul_f32_e32 v6, 0xbfb8aa3b, v226
	v_mul_f32_e32 v7, 0xbfb8aa3b, v227
	v_exp_f32_e32 v28, v28
	v_exp_f32_e32 v29, v29
	v_exp_f32_e32 v30, v30
	v_exp_f32_e32 v31, v31
	v_exp_f32_e32 v20, v20
	v_exp_f32_e32 v21, v21
	v_exp_f32_e32 v22, v22
	v_exp_f32_e32 v23, v23
	v_exp_f32_e32 v12, v12
	v_exp_f32_e32 v13, v13
	v_exp_f32_e32 v14, v14
	v_exp_f32_e32 v15, v15
	v_exp_f32_e32 v4, v4
	v_exp_f32_e32 v5, v5
	v_exp_f32_e32 v6, v6
	v_exp_f32_e32 v7, v7
	v_add_f32_e32 v28, 1.0, v28
	v_add_f32_e32 v29, 1.0, v29
	v_add_f32_e32 v30, 1.0, v30
	v_add_f32_e32 v31, 1.0, v31
	v_add_f32_e32 v20, 1.0, v20
	v_add_f32_e32 v21, 1.0, v21
	v_add_f32_e32 v22, 1.0, v22
	v_add_f32_e32 v23, 1.0, v23
	v_add_f32_e32 v12, 1.0, v12
	v_add_f32_e32 v13, 1.0, v13
	v_add_f32_e32 v14, 1.0, v14
	v_add_f32_e32 v15, 1.0, v15
	v_add_f32_e32 v4, 1.0, v4
	v_add_f32_e32 v5, 1.0, v5
	v_add_f32_e32 v6, 1.0, v6
	v_add_f32_e32 v7, 1.0, v7
	v_rcp_f32_e32 v28, v28
	v_rcp_f32_e32 v29, v29
	v_rcp_f32_e32 v30, v30
	v_rcp_f32_e32 v31, v31
	v_rcp_f32_e32 v20, v20
	v_rcp_f32_e32 v21, v21
	v_rcp_f32_e32 v22, v22
	v_rcp_f32_e32 v23, v23
	v_rcp_f32_e32 v12, v12
	v_rcp_f32_e32 v13, v13
	v_rcp_f32_e32 v14, v14
	v_rcp_f32_e32 v15, v15
	v_rcp_f32_e32 v4, v4
	v_rcp_f32_e32 v5, v5
	v_rcp_f32_e32 v6, v6
	v_rcp_f32_e32 v7, v7
	v_pk_mul_f32 v[176:177], v[176:177], v[28:29]
	v_pk_mul_f32 v[178:179], v[178:179], v[30:31]
	v_pk_mul_f32 v[180:181], v[180:181], v[20:21]
	v_pk_mul_f32 v[182:183], v[182:183], v[22:23]
	v_pk_mul_f32 v[184:185], v[184:185], v[12:13]
	v_pk_mul_f32 v[186:187], v[186:187], v[14:15]
	v_pk_mul_f32 v[224:225], v[224:225], v[4:5]
	v_pk_mul_f32 v[226:227], v[226:227], v[6:7]
	v_pk_mul_f32 v[176:177], v[24:25], v[176:177]
	v_pk_mul_f32 v[178:179], v[26:27], v[178:179]
	v_pk_mul_f32 v[180:181], v[16:17], v[180:181]
	v_pk_mul_f32 v[182:183], v[18:19], v[182:183]
	v_pk_mul_f32 v[184:185], v[8:9], v[184:185]
	v_pk_mul_f32 v[186:187], v[10:11], v[186:187]
	v_pk_mul_f32 v[224:225], v[0:1], v[224:225]
	v_pk_mul_f32 v[226:227], v[2:3], v[226:227]
	v_cvt_pk_bf16_f32 v28, v176, v177
	v_cvt_pk_bf16_f32 v29, v178, v179
	v_cvt_pk_bf16_f32 v20, v180, v181
	v_cvt_pk_bf16_f32 v21, v182, v183
	v_cvt_pk_bf16_f32 v12, v184, v185
	v_cvt_pk_bf16_f32 v13, v186, v187
	v_cvt_pk_bf16_f32 v4, v224, v225
	v_cvt_pk_bf16_f32 v5, v226, v227
	global_store_dwordx2 v174, v[28:29], s[0:1] offset:32
	v_add_u32_e32 v175, 0x2c00, v174
	global_store_dwordx2 v175, v[20:21], s[0:1] offset:32
	v_add_u32_e32 v175, 0x5800, v174
	global_store_dwordx2 v175, v[12:13], s[0:1] offset:32
	v_add_u32_e32 v175, 0x8400, v174
	global_store_dwordx2 v175, v[4:5], s[0:1] offset:32
	s_andn2_b64 vcc, exec, s[20:21]
	s_mov_b64 s[20:21], -1
	s_cbranch_vccnz .LBB0_1795
	s_andn2_b64 vcc, exec, s[2:3]
	s_cbranch_vccnz .LBB0_1794
	s_barrier
	s_branch .LBB0_1794
